# combined: first-iteration GEMM waits skipped + P2 per-trip load batching + FoX/SWA epilogue stores widened to dwordx4 + attention unit-end barrier moved after the epilogue
# speedup vs baseline: 1.0108x; 1.0092x over previous
; __device__ __forceinline__ unsigned cvt_pk_bf16(float lo, float hi) { f32x2_t v = {lo, hi}; bf16x2_t b = __builtin_convertvector(v, bf16x2_t); return __builtin_bit_cast(unsigned, b); }
; __device__ __forceinline__ float bf_lo(unsigned w) { return __uint_as_float(w << 16); }
; __device__ __forceinline__ float bf_hi(unsigned w) { return __uint_as_float(w & 0xffff0000u); }
; __device__ __forceinline__ float fast_rcp(float x) { return __builtin_amdgcn_rcpf(x); }
; __device__ __forceinline__ float swap_sum(float v) { auto rr = __builtin_amdgcn_permlane32_swap(__float_as_uint(v), __float_as_uint(v), false, false); return __uint_as_float(rr[0]) + __uint_as_float(rr[1]); }
; #define UNIT_END_BAR() asm volatile("s_waitcnt lgkmcnt(0)\n\ts_barrier" ::: "memory")
; __device__ __forceinline__ void attn_store_gated(const f32x16& o0, const f32x16& o1, float inv, const ZRegs& zr, bf16_t* urow, int hh) {
; #pragma unroll
;     for (int d0 = 0; d0 < 2; ++d0)
; #pragma unroll
;         for (int g = 0; g < 4; ++g) { const int d = 32 * d0 + 8 * g + 4 * hh; const u32x2 z = zr.z[d0][g]; const f32x16& o = d0 ? o1 : o0;
;             u32x2 w; w.x = cvt_pk_bf16(o[4 * g] * inv * bf_lo(z.x), o[4 * g + 1] * inv * bf_hi(z.x)); w.y = cvt_pk_bf16(o[4 * g + 2] * inv * bf_lo(z.y), o[4 * g + 3] * inv * bf_hi(z.y));
;             *(u32x2*)(urow + d) = w; }
; }
; __device__ __forceinline__ void fox_unit(LAS char* lds, int bh, int qb2, const bf16_t* H, const float* c, const unsigned* ctl, bf16_t* U, int tid) {
;     ...
;     UNIT_END_BAR();
;     ...
;     { ZRegs zr; load_z(zr, Hb + (size_t)qposA * HQ + C_FZ + h * 64, hh); attn_store_gated(oA0, oA1, fast_rcp(swap_sum(lA)), zr, U + ((size_t)b * SEQ + qposA) * 2048 + U_FOX + h * 64, hh); }
;     { ZRegs zr; load_z(zr, Hb + (size_t)qposB * HQ + C_FZ + h * 64, hh); attn_store_gated(oB0, oB1, fast_rcp(swap_sum(lB)), zr, U + ((size_t)b * SEQ + qposB) * 2048 + U_FOX + h * 64, hh); }
.LBB0_369:
	v_lshlrev_b32_e32 v0, 1, v150
	v_lshl_add_u64 v[66:67], v[160:161], 0, v[0:1]
	global_load_dwordx2 v[78:79], v[66:67], off offset:3072
	global_load_dwordx2 v[80:81], v[66:67], off offset:3088
	global_load_dwordx2 v[82:83], v[66:67], off offset:3104
	global_load_dwordx2 v[76:77], v[66:67], off offset:3120
	global_load_dwordx2 v[74:75], v[66:67], off offset:3136
	global_load_dwordx2 v[72:73], v[66:67], off offset:3152
	global_load_dwordx2 v[70:71], v[66:67], off offset:3168
	s_nop 0
	global_load_dwordx2 v[66:67], v[66:67], off offset:3184
	v_mov_b32_e32 v68, v212
	s_nop 1
	v_permlane32_swap_b32_e32 v212, v68
	v_add_f32_e32 v68, v212, v68
	v_rcp_f32_e32 v68, v68
	s_mov_b32 s47, s31
	v_lshl_add_u64 v[84:85], v[158:159], 0, s[46:47]
	v_lshlrev_b64 v[84:85], 12, v[84:85]
	v_mul_f32_e32 v50, v50, v68
	v_mul_f32_e32 v51, v51, v68
	v_lshl_add_u64 v[84:85], s[36:37], 0, v[84:85]
	v_lshl_add_u64 v[84:85], v[84:85], 0, s[30:31]
	v_mul_f32_e32 v34, v34, v68
	v_mul_f32_e32 v35, v35, v68
	v_mul_f32_e32 v36, v36, v68
	v_mul_f32_e32 v37, v37, v68
	s_waitcnt vmcnt(0)
	v_lshlrev_b32_e32 v86, 16, v78
	v_and_b32_e32 v87, 0xffff0000, v78
	v_mul_f32_e32 v50, v50, v86
	v_mul_f32_e32 v51, v51, v87
	s_nop 0
	v_cvt_pk_bf16_f32 v78, v50, v51
	v_mul_f32_e32 v50, v52, v68
	v_mul_f32_e32 v51, v53, v68
	v_lshlrev_b32_e32 v52, 16, v79
	v_and_b32_e32 v53, 0xffff0000, v79
	v_mul_f32_e32 v50, v50, v52
	v_mul_f32_e32 v51, v51, v53
	v_mul_f32_e32 v52, v54, v68
	v_mul_f32_e32 v53, v55, v68
	v_lshlrev_b32_e32 v54, 16, v80
	v_and_b32_e32 v55, 0xffff0000, v80
	v_mul_f32_e32 v52, v52, v54
	v_mul_f32_e32 v53, v53, v55
	v_mul_f32_e32 v54, v56, v68
	v_mul_f32_e32 v55, v57, v68
	v_lshlrev_b32_e32 v56, 16, v81
	v_and_b32_e32 v57, 0xffff0000, v81
	v_mul_f32_e32 v54, v54, v56
	v_mul_f32_e32 v55, v55, v57
	v_cvt_pk_bf16_f32 v79, v50, v51
	v_lshl_add_u64 v[50:51], v[84:85], 0, v[0:1]
	v_cvt_pk_bf16_f32 v52, v52, v53
	v_cvt_pk_bf16_f32 v53, v54, v55
	v_mov_b32_e32 v114, v52
	v_mov_b32_e32 v115, v53
	v_mul_f32_e32 v52, v58, v68
	v_mul_f32_e32 v53, v59, v68
	v_lshlrev_b32_e32 v54, 16, v82
	v_and_b32_e32 v55, 0xffff0000, v82
	v_mul_f32_e32 v52, v52, v54
	v_mul_f32_e32 v53, v53, v55
	v_mul_f32_e32 v54, v60, v68
	v_mul_f32_e32 v55, v61, v68
	v_lshlrev_b32_e32 v56, 16, v83
	v_and_b32_e32 v57, 0xffff0000, v83
	v_mul_f32_e32 v54, v54, v56
	v_mul_f32_e32 v55, v55, v57
	v_cvt_pk_bf16_f32 v52, v52, v53
	v_cvt_pk_bf16_f32 v53, v54, v55
	v_mov_b32_e32 v116, v52
	v_mov_b32_e32 v117, v53
	v_mul_f32_e32 v52, v62, v68
	v_mul_f32_e32 v53, v63, v68
	v_lshlrev_b32_e32 v54, 16, v76
	v_and_b32_e32 v55, 0xffff0000, v76
	v_mul_f32_e32 v52, v52, v54
	v_mul_f32_e32 v53, v53, v55
	v_mul_f32_e32 v54, v64, v68
	v_mul_f32_e32 v55, v65, v68
	v_lshlrev_b32_e32 v56, 16, v77
	v_and_b32_e32 v57, 0xffff0000, v77
	v_mul_f32_e32 v54, v54, v56
	v_mul_f32_e32 v55, v55, v57
	v_cvt_pk_bf16_f32 v52, v52, v53
	v_cvt_pk_bf16_f32 v53, v54, v55
	v_mov_b32_e32 v118, v52
	v_mov_b32_e32 v119, v53
	v_lshlrev_b32_e32 v52, 16, v74
	v_and_b32_e32 v53, 0xffff0000, v74
	v_mul_f32_e32 v34, v34, v52
	v_mul_f32_e32 v35, v35, v53
	v_lshlrev_b32_e32 v52, 16, v75
	v_and_b32_e32 v53, 0xffff0000, v75
	v_mul_f32_e32 v36, v36, v52
	v_mul_f32_e32 v37, v37, v53
	v_cvt_pk_bf16_f32 v34, v34, v35
	v_cvt_pk_bf16_f32 v35, v36, v37
	v_mov_b32_e32 v120, v34
	v_mov_b32_e32 v121, v35
	v_mul_f32_e32 v34, v38, v68
	v_mul_f32_e32 v35, v39, v68
	v_lshlrev_b32_e32 v36, 16, v72
	v_and_b32_e32 v37, 0xffff0000, v72
	v_mul_f32_e32 v34, v34, v36
	v_mul_f32_e32 v35, v35, v37
	v_mul_f32_e32 v36, v40, v68
	v_mul_f32_e32 v37, v41, v68
	v_lshlrev_b32_e32 v38, 16, v73
	v_and_b32_e32 v39, 0xffff0000, v73
	v_mul_f32_e32 v36, v36, v38
	v_mul_f32_e32 v37, v37, v39
	v_cvt_pk_bf16_f32 v34, v34, v35
	v_cvt_pk_bf16_f32 v35, v36, v37
	v_mov_b32_e32 v122, v34
	v_mov_b32_e32 v123, v35
	v_mul_f32_e32 v34, v42, v68
	v_mul_f32_e32 v35, v43, v68
	v_lshlrev_b32_e32 v36, 16, v70
	v_and_b32_e32 v37, 0xffff0000, v70
	v_mul_f32_e32 v34, v34, v36
	v_mul_f32_e32 v35, v35, v37
	v_mul_f32_e32 v36, v44, v68
	v_mul_f32_e32 v37, v45, v68
	v_lshlrev_b32_e32 v38, 16, v71
	v_and_b32_e32 v39, 0xffff0000, v71
	v_mul_f32_e32 v36, v36, v38
	v_mul_f32_e32 v37, v37, v39
	v_cvt_pk_bf16_f32 v34, v34, v35
	v_cvt_pk_bf16_f32 v35, v36, v37
	v_mov_b32_e32 v124, v34
	v_mov_b32_e32 v125, v35
	v_mul_f32_e32 v34, v46, v68
	v_mul_f32_e32 v35, v47, v68
	v_lshlrev_b32_e32 v36, 16, v66
	v_and_b32_e32 v37, 0xffff0000, v66
	v_mul_f32_e32 v34, v34, v36
	v_mul_f32_e32 v35, v35, v37
	v_mul_f32_e32 v36, v48, v68
	v_mul_f32_e32 v37, v49, v68
	v_lshlrev_b32_e32 v38, 16, v67
	v_and_b32_e32 v39, 0xffff0000, v67
	v_mul_f32_e32 v36, v36, v38
	v_mul_f32_e32 v37, v37, v39
	v_cvt_pk_bf16_f32 v34, v34, v35
	v_cvt_pk_bf16_f32 v35, v36, v37
	v_mov_b32_e32 v112, v78
	v_mov_b32_e32 v113, v79
	v_mov_b32_e32 v126, v34
	v_mov_b32_e32 v127, v35
	v_mbcnt_lo_u32_b32 v130, -1, 0
	v_mbcnt_hi_u32_b32 v130, -1, v130
	v_and_b32_e32 v130, 32, v130
	v_lshrrev_b32_e32 v130, 2, v130
	v_mov_b32_e32 v131, 0
	v_lshl_add_u64 v[128:129], v[50:51], 0, v[130:131]
	v_permlane32_swap_b32_e32 v112, v114
	v_permlane32_swap_b32_e32 v113, v115
	global_store_dwordx4 v[128:129], v[112:115], off
	v_permlane32_swap_b32_e32 v116, v118
	v_permlane32_swap_b32_e32 v117, v119
	global_store_dwordx4 v[128:129], v[116:119], off offset:32
	v_permlane32_swap_b32_e32 v120, v122
	v_permlane32_swap_b32_e32 v121, v123
	global_store_dwordx4 v[128:129], v[120:123], off offset:64
	v_permlane32_swap_b32_e32 v124, v126
	v_permlane32_swap_b32_e32 v125, v127
	global_store_dwordx4 v[128:129], v[124:127], off offset:96
	v_lshl_add_u64 v[34:35], v[156:157], 0, v[0:1]
	global_load_dwordx2 v[46:47], v[34:35], off offset:3072
	global_load_dwordx2 v[48:49], v[34:35], off offset:3088
	global_load_dwordx2 v[50:51], v[34:35], off offset:3104
	global_load_dwordx2 v[44:45], v[34:35], off offset:3120
	global_load_dwordx2 v[42:43], v[34:35], off offset:3136
	global_load_dwordx2 v[40:41], v[34:35], off offset:3152
	global_load_dwordx2 v[38:39], v[34:35], off offset:3168
	s_nop 0
	global_load_dwordx2 v[34:35], v[34:35], off offset:3184
	v_mov_b32_e32 v36, v194
	s_nop 1
	v_permlane32_swap_b32_e32 v194, v36
	v_add_f32_e32 v36, v194, v36
	v_rcp_f32_e32 v36, v36
	v_lshl_add_u64 v[52:53], v[154:155], 0, s[46:47]
	v_lshlrev_b64 v[52:53], 12, v[52:53]
	v_lshl_add_u64 v[52:53], s[36:37], 0, v[52:53]
	v_mul_f32_e32 v18, v18, v36
	v_mul_f32_e32 v19, v19, v36
	v_lshl_add_u64 v[52:53], v[52:53], 0, s[30:31]
	v_mul_f32_e32 v2, v2, v36
	v_mul_f32_e32 v3, v3, v36
	v_mul_f32_e32 v4, v4, v36
	v_mul_f32_e32 v5, v5, v36
	s_waitcnt vmcnt(0)
; __device__ __forceinline__ unsigned cvt_pk_bf16(float lo, float hi) { f32x2_t v = {lo, hi}; bf16x2_t b = __builtin_convertvector(v, bf16x2_t); return __builtin_bit_cast(unsigned, b); }
; __device__ __forceinline__ float bf_lo(unsigned w) { return __uint_as_float(w << 16); }
; __device__ __forceinline__ float bf_hi(unsigned w) { return __uint_as_float(w & 0xffff0000u); }
; __device__ __forceinline__ float fast_rcp(float x) { return __builtin_amdgcn_rcpf(x); }
; __device__ __forceinline__ float swap_sum(float v) { auto rr = __builtin_amdgcn_permlane32_swap(__float_as_uint(v), __float_as_uint(v), false, false); return __uint_as_float(rr[0]) + __uint_as_float(rr[1]); }
; #define UNIT_END_BAR() asm volatile("s_waitcnt lgkmcnt(0)\n\ts_barrier" ::: "memory")
; __device__ __forceinline__ void attn_store_gated(const f32x16& o0, const f32x16& o1, float inv, const ZRegs& zr, bf16_t* urow, int hh) {
; #pragma unroll
;     for (int d0 = 0; d0 < 2; ++d0)
; #pragma unroll
;         for (int g = 0; g < 4; ++g) { const int d = 32 * d0 + 8 * g + 4 * hh; const u32x2 z = zr.z[d0][g]; const f32x16& o = d0 ? o1 : o0;
;             u32x2 w; w.x = cvt_pk_bf16(o[4 * g] * inv * bf_lo(z.x), o[4 * g + 1] * inv * bf_hi(z.x)); w.y = cvt_pk_bf16(o[4 * g + 2] * inv * bf_lo(z.y), o[4 * g + 3] * inv * bf_hi(z.y));
;             *(u32x2*)(urow + d) = w; }
; }
; __device__ __forceinline__ void fox_unit(LAS char* lds, int bh, int qb2, const bf16_t* H, const float* c, const unsigned* ctl, bf16_t* U, int tid) {
;     ...
;     UNIT_END_BAR();
;     ...
;     { ZRegs zr; load_z(zr, Hb + (size_t)qposA * HQ + C_FZ + h * 64, hh); attn_store_gated(oA0, oA1, fast_rcp(swap_sum(lA)), zr, U + ((size_t)b * SEQ + qposA) * 2048 + U_FOX + h * 64, hh); }
;     { ZRegs zr; load_z(zr, Hb + (size_t)qposB * HQ + C_FZ + h * 64, hh); attn_store_gated(oB0, oB1, fast_rcp(swap_sum(lB)), zr, U + ((size_t)b * SEQ + qposB) * 2048 + U_FOX + h * 64, hh); }
	v_lshlrev_b32_e32 v54, 16, v46
	v_and_b32_e32 v55, 0xffff0000, v46
	v_mul_f32_e32 v18, v18, v54
	v_mul_f32_e32 v19, v19, v55
	s_nop 0
	v_cvt_pk_bf16_f32 v46, v18, v19
	v_mul_f32_e32 v18, v20, v36
	v_mul_f32_e32 v19, v21, v36
	v_lshlrev_b32_e32 v20, 16, v47
	v_and_b32_e32 v21, 0xffff0000, v47
	v_mul_f32_e32 v18, v18, v20
	v_mul_f32_e32 v19, v19, v21
	v_mul_f32_e32 v20, v22, v36
	v_mul_f32_e32 v21, v23, v36
	v_lshlrev_b32_e32 v22, 16, v48
	v_and_b32_e32 v23, 0xffff0000, v48
	v_mul_f32_e32 v20, v20, v22
	v_mul_f32_e32 v21, v21, v23
	v_mul_f32_e32 v22, v24, v36
	v_mul_f32_e32 v23, v25, v36
	v_lshlrev_b32_e32 v24, 16, v49
	v_and_b32_e32 v25, 0xffff0000, v49
	v_mul_f32_e32 v22, v22, v24
	v_mul_f32_e32 v23, v23, v25
	v_cvt_pk_bf16_f32 v47, v18, v19
	v_lshl_add_u64 v[18:19], v[52:53], 0, v[0:1]
	v_cvt_pk_bf16_f32 v20, v20, v21
	v_cvt_pk_bf16_f32 v21, v22, v23
	v_mov_b32_e32 v114, v20
	v_mov_b32_e32 v115, v21
	v_mul_f32_e32 v20, v26, v36
	v_mul_f32_e32 v21, v27, v36
	v_lshlrev_b32_e32 v22, 16, v50
	v_and_b32_e32 v23, 0xffff0000, v50
	v_mul_f32_e32 v20, v20, v22
	v_mul_f32_e32 v21, v21, v23
	v_mul_f32_e32 v22, v28, v36
	v_mul_f32_e32 v23, v29, v36
	v_lshlrev_b32_e32 v24, 16, v51
	v_and_b32_e32 v25, 0xffff0000, v51
	v_mul_f32_e32 v22, v22, v24
	v_mul_f32_e32 v23, v23, v25
	v_cvt_pk_bf16_f32 v20, v20, v21
	v_cvt_pk_bf16_f32 v21, v22, v23
	v_mov_b32_e32 v116, v20
	v_mov_b32_e32 v117, v21
	v_mul_f32_e32 v20, v30, v36
	v_mul_f32_e32 v21, v31, v36
	v_lshlrev_b32_e32 v22, 16, v44
	v_and_b32_e32 v23, 0xffff0000, v44
	v_mul_f32_e32 v20, v20, v22
	v_mul_f32_e32 v21, v21, v23
	v_mul_f32_e32 v22, v32, v36
	v_mul_f32_e32 v23, v33, v36
	v_lshlrev_b32_e32 v24, 16, v45
	v_and_b32_e32 v25, 0xffff0000, v45
	v_mul_f32_e32 v22, v22, v24
	v_mul_f32_e32 v23, v23, v25
	v_cvt_pk_bf16_f32 v20, v20, v21
	v_cvt_pk_bf16_f32 v21, v22, v23
	v_mov_b32_e32 v118, v20
	v_mov_b32_e32 v119, v21
	v_lshlrev_b32_e32 v20, 16, v42
	v_and_b32_e32 v21, 0xffff0000, v42
	v_mul_f32_e32 v2, v2, v20
	v_mul_f32_e32 v3, v3, v21
	v_lshlrev_b32_e32 v20, 16, v43
	v_and_b32_e32 v21, 0xffff0000, v43
	v_mul_f32_e32 v4, v4, v20
	v_mul_f32_e32 v5, v5, v21
	v_cvt_pk_bf16_f32 v2, v2, v3
	v_cvt_pk_bf16_f32 v3, v4, v5
	v_mov_b32_e32 v120, v2
	v_mov_b32_e32 v121, v3
	v_mul_f32_e32 v2, v6, v36
	v_mul_f32_e32 v3, v7, v36
	v_lshlrev_b32_e32 v4, 16, v40
	v_and_b32_e32 v5, 0xffff0000, v40
	v_mul_f32_e32 v2, v2, v4
	v_mul_f32_e32 v3, v3, v5
	v_mul_f32_e32 v4, v8, v36
	v_mul_f32_e32 v5, v9, v36
	v_lshlrev_b32_e32 v6, 16, v41
	v_and_b32_e32 v7, 0xffff0000, v41
	v_mul_f32_e32 v4, v4, v6
	v_mul_f32_e32 v5, v5, v7
	v_cvt_pk_bf16_f32 v2, v2, v3
	v_cvt_pk_bf16_f32 v3, v4, v5
	v_mov_b32_e32 v122, v2
	v_mov_b32_e32 v123, v3
	v_mul_f32_e32 v2, v10, v36
	v_mul_f32_e32 v3, v11, v36
	v_lshlrev_b32_e32 v4, 16, v38
	v_and_b32_e32 v5, 0xffff0000, v38
	v_mul_f32_e32 v2, v2, v4
	v_mul_f32_e32 v3, v3, v5
	v_mul_f32_e32 v4, v12, v36
	v_mul_f32_e32 v5, v13, v36
	v_lshlrev_b32_e32 v6, 16, v39
	v_and_b32_e32 v7, 0xffff0000, v39
	v_mul_f32_e32 v4, v4, v6
	v_mul_f32_e32 v5, v5, v7
	v_cvt_pk_bf16_f32 v2, v2, v3
	v_cvt_pk_bf16_f32 v3, v4, v5
	v_mov_b32_e32 v124, v2
	v_mov_b32_e32 v125, v3
	v_mul_f32_e32 v2, v14, v36
	v_mul_f32_e32 v3, v15, v36
	v_lshlrev_b32_e32 v4, 16, v34
	v_and_b32_e32 v5, 0xffff0000, v34
	v_mul_f32_e32 v2, v2, v4
	v_mul_f32_e32 v3, v3, v5
	v_mul_f32_e32 v4, v16, v36
	v_mul_f32_e32 v5, v17, v36
	v_lshlrev_b32_e32 v6, 16, v35
	v_and_b32_e32 v7, 0xffff0000, v35
	v_mul_f32_e32 v4, v4, v6
	v_mul_f32_e32 v5, v5, v7
	v_cvt_pk_bf16_f32 v2, v2, v3
	v_cvt_pk_bf16_f32 v3, v4, v5
	v_mov_b32_e32 v112, v46
	v_mov_b32_e32 v113, v47
	v_mov_b32_e32 v126, v2
	v_mov_b32_e32 v127, v3
	v_mbcnt_lo_u32_b32 v130, -1, 0
	v_mbcnt_hi_u32_b32 v130, -1, v130
	v_and_b32_e32 v130, 32, v130
	v_lshrrev_b32_e32 v130, 2, v130
	v_mov_b32_e32 v131, 0
	v_lshl_add_u64 v[128:129], v[18:19], 0, v[130:131]
	v_permlane32_swap_b32_e32 v112, v114
	v_permlane32_swap_b32_e32 v113, v115
	global_store_dwordx4 v[128:129], v[112:115], off
	v_permlane32_swap_b32_e32 v116, v118
	v_permlane32_swap_b32_e32 v117, v119
	global_store_dwordx4 v[128:129], v[116:119], off offset:32
	v_permlane32_swap_b32_e32 v120, v122
	v_permlane32_swap_b32_e32 v121, v123
	global_store_dwordx4 v[128:129], v[120:123], off offset:64
	v_permlane32_swap_b32_e32 v124, v126
	v_permlane32_swap_b32_e32 v125, v127
	global_store_dwordx4 v[128:129], v[124:127], off offset:96
.LBB0_370:
	s_waitcnt lgkmcnt(0)
	s_barrier
	s_add_i32 s7, s7, s56
	s_cmp_ge_i32 s7, s61
	s_cbranch_scc1 .LBB0_577

; __device__ __forceinline__ unsigned cvt_pk_bf16(float lo, float hi) { f32x2_t v = {lo, hi}; bf16x2_t b = __builtin_convertvector(v, bf16x2_t); return __builtin_bit_cast(unsigned, b); }
; __device__ __forceinline__ float bf_lo(unsigned w) { return __uint_as_float(w << 16); }
; __device__ __forceinline__ float bf_hi(unsigned w) { return __uint_as_float(w & 0xffff0000u); }
; __device__ __forceinline__ float fast_exp2(float x) { return __builtin_amdgcn_exp2f(x); }
; __device__ __forceinline__ float fast_rcp(float x) { return __builtin_amdgcn_rcpf(x); }
; __device__ __forceinline__ float swap_sum(float v) { auto rr = __builtin_amdgcn_permlane32_swap(__float_as_uint(v), __float_as_uint(v), false, false); return __uint_as_float(rr[0]) + __uint_as_float(rr[1]); }
; __device__ __forceinline__ void attn_store_gated(const f32x16& o0, const f32x16& o1, float inv, const ZRegs& zr, bf16_t* urow, int hh) {
; #pragma unroll
;     for (int d0 = 0; d0 < 2; ++d0)
; #pragma unroll
;         for (int g = 0; g < 4; ++g) { const int d = 32 * d0 + 8 * g + 4 * hh; const u32x2 z = zr.z[d0][g]; const f32x16& o = d0 ? o1 : o0;
;             u32x2 w; w.x = cvt_pk_bf16(o[4 * g] * inv * bf_lo(z.x), o[4 * g + 1] * inv * bf_hi(z.x)); w.y = cvt_pk_bf16(o[4 * g + 2] * inv * bf_lo(z.y), o[4 * g + 3] * inv * bf_hi(z.y));
;             *(u32x2*)(urow + d) = w; }
; }
; __device__ __forceinline__ void swa_unit(LAS char* lds, int b, int kvh, int qi, const bf16_t* H, const float* sinks, bf16_t* U, int tid) {
;     ...
;     { const float lt = swap_sum(lA), sinkp = sinkv * LOG2E + slope2 * (float)(qposA - q0);
;       const float mf = fmaxf(mA, sinkp), sc = fast_exp2(mA - mf), inv = sc * fast_rcp(lt * sc + fast_exp2(sinkp - mf));
;       ZRegs zr; load_z(zr, Hb + (size_t)qposA * HQ + C_SZ + hq * 64, hh); attn_store_gated(oA0, oA1, inv, zr, U + ((size_t)b * SEQ + qposA) * 2048 + U_SWA + hq * 64, hh); }
;     { const float lt = swap_sum(lB), sinkp = sinkv * LOG2E + slope2 * (float)(qposB - q0);
;       const float mf = fmaxf(mB, sinkp), sc = fast_exp2(mB - mf), inv = sc * fast_rcp(lt * sc + fast_exp2(sinkp - mf));
;       ZRegs zr; load_z(zr, Hb + (size_t)qposB * HQ + C_SZ + hq * 64, hh); attn_store_gated(oB0, oB1, inv, zr, U + ((size_t)b * SEQ + qposB) * 2048 + U_SWA + hq * 64, hh); }
.LBB0_436:
	v_subrev_u32_e32 v66, s42, v160
	v_cvt_f32_i32_e32 v194, v66
	v_mov_b32_e32 v159, v207
	v_max_f32_e32 v68, v210, v210
	v_mov_b32_e32 v0, v211
	v_mul_f32_e32 v66, v158, v194
	v_mul_f32_e32 v67, v159, v195
	s_nop 0
	v_permlane32_swap_b32_e32 v211, v0
	v_add_f32_e32 v66, v66, v67
	v_max_f32_e32 v68, v68, v66
	v_sub_f32_e32 v69, v210, v68
	v_sub_f32_e32 v66, v66, v68
	v_exp_f32_e32 v69, v69
	v_exp_f32_e32 v66, v66
	v_add_f32_e32 v0, v211, v0
	s_mov_b64 s[0:1], 0x1600
	v_fmac_f32_e32 v66, v69, v0
	v_rcp_f32_e32 v0, v66
	s_lshl_b64 s[18:19], s[48:49], 14
	v_readlane_b32 s52, v254, 59
	v_readlane_b32 s53, v254, 60
	v_mul_f32_e32 v66, v69, v0
	v_lshlrev_b32_e32 v0, 1, v150
	v_lshl_add_u64 v[68:69], v[162:163], 0, v[0:1]
	v_lshl_add_u64 v[80:81], v[68:69], 0, s[0:1]
	v_add_co_u32_e32 v68, vcc, s75, v68
	v_mul_f32_e32 v50, v50, v66
	v_mul_f32_e32 v51, v51, v66
	s_nop 0
	v_addc_co_u32_e32 v69, vcc, 0, v69, vcc
	global_load_dwordx2 v[82:83], v[68:69], off offset:1536
	global_load_dwordx2 v[84:85], v[80:81], off offset:16
	global_load_dwordx2 v[78:79], v[80:81], off offset:32
	global_load_dwordx2 v[76:77], v[80:81], off offset:48
	global_load_dwordx2 v[74:75], v[80:81], off offset:64
	global_load_dwordx2 v[72:73], v[80:81], off offset:80
	global_load_dwordx2 v[70:71], v[80:81], off offset:96
	global_load_dwordx2 v[68:69], v[80:81], off offset:112
	v_mov_b32_e32 v81, s19
	v_or_b32_e32 v80, s18, v160
	v_lshlrev_b64 v[80:81], 12, v[80:81]
	v_lshl_add_u64 v[80:81], s[36:37], 0, v[80:81]
	v_lshl_add_u64 v[80:81], v[80:81], 0, s[46:47]
	v_mul_f32_e32 v34, v34, v66
	v_mul_f32_e32 v35, v35, v66
	v_mul_f32_e32 v36, v36, v66
	v_mul_f32_e32 v37, v37, v66
	s_mov_b32 s33, 0x42fc0000
	s_waitcnt vmcnt(0)
	v_lshlrev_b32_e32 v86, 16, v82
	v_and_b32_e32 v87, 0xffff0000, v82
	v_mul_f32_e32 v50, v50, v86
	v_mul_f32_e32 v51, v51, v87
	s_nop 0
	v_cvt_pk_bf16_f32 v82, v50, v51
	v_mul_f32_e32 v50, v52, v66
	v_mul_f32_e32 v51, v53, v66
	v_lshlrev_b32_e32 v52, 16, v83
	v_and_b32_e32 v53, 0xffff0000, v83
	v_mul_f32_e32 v50, v50, v52
	v_mul_f32_e32 v51, v51, v53
	v_mul_f32_e32 v52, v54, v66
	v_mul_f32_e32 v53, v55, v66
	v_lshlrev_b32_e32 v54, 16, v84
	v_and_b32_e32 v55, 0xffff0000, v84
	v_mul_f32_e32 v52, v52, v54
	v_mul_f32_e32 v53, v53, v55
	v_mul_f32_e32 v54, v56, v66
	v_mul_f32_e32 v55, v57, v66
	v_lshlrev_b32_e32 v56, 16, v85
	v_and_b32_e32 v57, 0xffff0000, v85
	v_mul_f32_e32 v54, v54, v56
	v_mul_f32_e32 v55, v55, v57
	v_cvt_pk_bf16_f32 v83, v50, v51
	v_lshl_add_u64 v[50:51], v[80:81], 0, v[0:1]
	v_cvt_pk_bf16_f32 v52, v52, v53
	v_cvt_pk_bf16_f32 v53, v54, v55
	v_mov_b32_e32 v114, v52
	v_mov_b32_e32 v115, v53
	v_mul_f32_e32 v52, v58, v66
	v_mul_f32_e32 v53, v59, v66
	v_lshlrev_b32_e32 v54, 16, v78
	v_and_b32_e32 v55, 0xffff0000, v78
	v_mul_f32_e32 v52, v52, v54
	v_mul_f32_e32 v53, v53, v55
	v_mul_f32_e32 v54, v60, v66
	v_mul_f32_e32 v55, v61, v66
	v_lshlrev_b32_e32 v56, 16, v79
	v_and_b32_e32 v57, 0xffff0000, v79
	v_mul_f32_e32 v54, v54, v56
	v_mul_f32_e32 v55, v55, v57
	v_cvt_pk_bf16_f32 v52, v52, v53
	v_cvt_pk_bf16_f32 v53, v54, v55
	v_mov_b32_e32 v116, v52
	v_mov_b32_e32 v117, v53
	v_mul_f32_e32 v52, v62, v66
	v_mul_f32_e32 v53, v63, v66
	v_lshlrev_b32_e32 v54, 16, v76
	v_and_b32_e32 v55, 0xffff0000, v76
	v_mul_f32_e32 v52, v52, v54
	v_mul_f32_e32 v53, v53, v55
	v_mul_f32_e32 v54, v64, v66
	v_mul_f32_e32 v55, v65, v66
	v_lshlrev_b32_e32 v56, 16, v77
	v_and_b32_e32 v57, 0xffff0000, v77
	v_mul_f32_e32 v54, v54, v56
	v_mul_f32_e32 v55, v55, v57
	v_cvt_pk_bf16_f32 v52, v52, v53
	v_cvt_pk_bf16_f32 v53, v54, v55
	v_mov_b32_e32 v118, v52
	v_mov_b32_e32 v119, v53
	v_lshlrev_b32_e32 v52, 16, v74
	v_and_b32_e32 v53, 0xffff0000, v74
	v_mul_f32_e32 v34, v34, v52
	v_mul_f32_e32 v35, v35, v53
	v_lshlrev_b32_e32 v52, 16, v75
	v_and_b32_e32 v53, 0xffff0000, v75
	v_mul_f32_e32 v36, v36, v52
	v_mul_f32_e32 v37, v37, v53
	v_cvt_pk_bf16_f32 v34, v34, v35
	v_cvt_pk_bf16_f32 v35, v36, v37
	v_mov_b32_e32 v120, v34
	v_mov_b32_e32 v121, v35
	v_mul_f32_e32 v34, v38, v66
	v_mul_f32_e32 v35, v39, v66
	v_lshlrev_b32_e32 v36, 16, v72
	v_and_b32_e32 v37, 0xffff0000, v72
	v_mul_f32_e32 v34, v34, v36
	v_mul_f32_e32 v35, v35, v37
	v_mul_f32_e32 v36, v40, v66
	v_mul_f32_e32 v37, v41, v66
	v_lshlrev_b32_e32 v38, 16, v73
	v_and_b32_e32 v39, 0xffff0000, v73
	v_mul_f32_e32 v36, v36, v38
	v_mul_f32_e32 v37, v37, v39
	v_cvt_pk_bf16_f32 v34, v34, v35
	v_cvt_pk_bf16_f32 v35, v36, v37
	v_mov_b32_e32 v122, v34
	v_mov_b32_e32 v123, v35
	v_mul_f32_e32 v34, v42, v66
	v_mul_f32_e32 v35, v43, v66
	v_lshlrev_b32_e32 v36, 16, v70
	v_and_b32_e32 v37, 0xffff0000, v70
	v_mul_f32_e32 v34, v34, v36
	v_mul_f32_e32 v35, v35, v37
	v_mul_f32_e32 v36, v44, v66
	v_mul_f32_e32 v37, v45, v66
	v_lshlrev_b32_e32 v38, 16, v71
	v_and_b32_e32 v39, 0xffff0000, v71
	v_mul_f32_e32 v36, v36, v38
	v_mul_f32_e32 v37, v37, v39
	v_cvt_pk_bf16_f32 v34, v34, v35
	v_cvt_pk_bf16_f32 v35, v36, v37
	v_mov_b32_e32 v124, v34
	v_mov_b32_e32 v125, v35
	v_mul_f32_e32 v34, v46, v66
	v_mul_f32_e32 v35, v47, v66
	v_lshlrev_b32_e32 v36, 16, v68
	v_and_b32_e32 v37, 0xffff0000, v68
	v_mul_f32_e32 v34, v34, v36
	v_mul_f32_e32 v35, v35, v37
	v_mul_f32_e32 v36, v48, v66
	v_mul_f32_e32 v37, v49, v66
	v_lshlrev_b32_e32 v38, 16, v69
	v_and_b32_e32 v39, 0xffff0000, v69
	v_mul_f32_e32 v36, v36, v38
	v_mul_f32_e32 v37, v37, v39
	v_cvt_pk_bf16_f32 v34, v34, v35
	v_cvt_pk_bf16_f32 v35, v36, v37
	v_mov_b32_e32 v126, v34
	v_mov_b32_e32 v127, v35
	v_subrev_u32_e32 v35, s42, v154
	v_cvt_f32_i32_e32 v35, v35
	v_mov_b32_e32 v34, v161
	s_nop 1
	v_permlane32_swap_b32_e32 v161, v34
	v_fmac_f32_e32 v67, v158, v35
	v_max_f32_e32 v35, v155, v155
	v_max_f32_e32 v35, v35, v67
; __device__ __forceinline__ unsigned cvt_pk_bf16(float lo, float hi) { f32x2_t v = {lo, hi}; bf16x2_t b = __builtin_convertvector(v, bf16x2_t); return __builtin_bit_cast(unsigned, b); }
; __device__ __forceinline__ float bf_lo(unsigned w) { return __uint_as_float(w << 16); }
; __device__ __forceinline__ float bf_hi(unsigned w) { return __uint_as_float(w & 0xffff0000u); }
; __device__ __forceinline__ float fast_exp2(float x) { return __builtin_amdgcn_exp2f(x); }
; __device__ __forceinline__ float fast_rcp(float x) { return __builtin_amdgcn_rcpf(x); }
; __device__ __forceinline__ float swap_sum(float v) { auto rr = __builtin_amdgcn_permlane32_swap(__float_as_uint(v), __float_as_uint(v), false, false); return __uint_as_float(rr[0]) + __uint_as_float(rr[1]); }
; __device__ __forceinline__ void attn_store_gated(const f32x16& o0, const f32x16& o1, float inv, const ZRegs& zr, bf16_t* urow, int hh) {
; #pragma unroll
;     for (int d0 = 0; d0 < 2; ++d0)
; #pragma unroll
;         for (int g = 0; g < 4; ++g) { const int d = 32 * d0 + 8 * g + 4 * hh; const u32x2 z = zr.z[d0][g]; const f32x16& o = d0 ? o1 : o0;
;             u32x2 w; w.x = cvt_pk_bf16(o[4 * g] * inv * bf_lo(z.x), o[4 * g + 1] * inv * bf_hi(z.x)); w.y = cvt_pk_bf16(o[4 * g + 2] * inv * bf_lo(z.y), o[4 * g + 3] * inv * bf_hi(z.y));
;             *(u32x2*)(urow + d) = w; }
; }
; __device__ __forceinline__ void swa_unit(LAS char* lds, int b, int kvh, int qi, const bf16_t* H, const float* sinks, bf16_t* U, int tid) {
;     ...
;     { const float lt = swap_sum(lB), sinkp = sinkv * LOG2E + slope2 * (float)(qposB - q0);
;       const float mf = fmaxf(mB, sinkp), sc = fast_exp2(mB - mf), inv = sc * fast_rcp(lt * sc + fast_exp2(sinkp - mf));
;       ZRegs zr; load_z(zr, Hb + (size_t)qposB * HQ + C_SZ + hq * 64, hh); attn_store_gated(oB0, oB1, inv, zr, U + ((size_t)b * SEQ + qposB) * 2048 + U_SWA + hq * 64, hh); }
	v_sub_f32_e32 v36, v155, v35
	v_sub_f32_e32 v35, v67, v35
	v_exp_f32_e32 v36, v36
	v_exp_f32_e32 v35, v35
	v_add_f32_e32 v34, v161, v34
	v_mov_b32_e32 v112, v82
	v_mov_b32_e32 v113, v83
	v_mbcnt_lo_u32_b32 v130, -1, 0
	v_mbcnt_hi_u32_b32 v130, -1, v130
	v_and_b32_e32 v130, 32, v130
	v_lshrrev_b32_e32 v130, 2, v130
	v_mov_b32_e32 v131, 0
	v_lshl_add_u64 v[128:129], v[50:51], 0, v[130:131]
	v_permlane32_swap_b32_e32 v112, v114
	v_permlane32_swap_b32_e32 v113, v115
	global_store_dwordx4 v[128:129], v[112:115], off offset:1024
	v_permlane32_swap_b32_e32 v116, v118
	v_permlane32_swap_b32_e32 v117, v119
	global_store_dwordx4 v[128:129], v[116:119], off offset:1056
	v_permlane32_swap_b32_e32 v120, v122
	v_permlane32_swap_b32_e32 v121, v123
	global_store_dwordx4 v[128:129], v[120:123], off offset:1088
	v_permlane32_swap_b32_e32 v124, v126
	v_permlane32_swap_b32_e32 v125, v127
	global_store_dwordx4 v[128:129], v[124:127], off offset:1120
	v_mov_b32_e32 v53, s19
	v_fmac_f32_e32 v35, v36, v34
	v_rcp_f32_e32 v34, v35
	v_or_b32_e32 v52, s18, v154
	v_lshlrev_b64 v[52:53], 12, v[52:53]
	v_lshl_add_u64 v[52:53], s[36:37], 0, v[52:53]
	v_mul_f32_e32 v34, v36, v34
	v_lshl_add_u64 v[36:37], v[156:157], 0, v[0:1]
	v_lshl_add_u64 v[38:39], v[36:37], 0, s[0:1]
	v_add_co_u32_e32 v36, vcc, s75, v36
	v_mul_f32_e32 v18, v18, v34
	v_mul_f32_e32 v19, v19, v34
	s_nop 0
	v_addc_co_u32_e32 v37, vcc, 0, v37, vcc
	global_load_dwordx2 v[36:37], v[36:37], off offset:1536
	s_nop 0
	global_load_dwordx2 v[40:41], v[38:39], off offset:16
	global_load_dwordx2 v[42:43], v[38:39], off offset:32
	global_load_dwordx2 v[44:45], v[38:39], off offset:48
	global_load_dwordx2 v[46:47], v[38:39], off offset:64
	global_load_dwordx2 v[48:49], v[38:39], off offset:80
	global_load_dwordx2 v[50:51], v[38:39], off offset:96
	s_nop 0
	global_load_dwordx2 v[38:39], v[38:39], off offset:112
	v_mul_f32_e32 v20, v20, v34
	v_mul_f32_e32 v21, v21, v34
	v_lshl_add_u64 v[52:53], v[52:53], 0, s[46:47]
	v_mul_f32_e32 v2, v2, v34
	v_mul_f32_e32 v3, v3, v34
	v_mul_f32_e32 v4, v4, v34
	v_mul_f32_e32 v5, v5, v34
	s_mov_b64 s[18:19], 0
	s_waitcnt vmcnt(0)
	v_lshlrev_b32_e32 v54, 16, v36
	v_and_b32_e32 v55, 0xffff0000, v36
	v_lshlrev_b32_e32 v36, 16, v37
	v_and_b32_e32 v37, 0xffff0000, v37
	v_mul_f32_e32 v18, v18, v54
	v_mul_f32_e32 v19, v19, v55
	v_mul_f32_e32 v20, v20, v36
	v_mul_f32_e32 v21, v21, v37
	v_cvt_pk_bf16_f32 v18, v18, v19
	v_cvt_pk_bf16_f32 v19, v20, v21
	v_lshl_add_u64 v[20:21], v[52:53], 0, v[0:1]
	v_mov_b32_e32 v112, v18
	v_mov_b32_e32 v113, v19
	v_mul_f32_e32 v18, v22, v34
	v_mul_f32_e32 v19, v23, v34
	v_lshlrev_b32_e32 v22, 16, v40
	v_and_b32_e32 v23, 0xffff0000, v40
	v_mul_f32_e32 v18, v18, v22
	v_mul_f32_e32 v19, v19, v23
	v_mul_f32_e32 v22, v24, v34
	v_mul_f32_e32 v23, v25, v34
	v_lshlrev_b32_e32 v24, 16, v41
	v_and_b32_e32 v25, 0xffff0000, v41
	v_mul_f32_e32 v22, v22, v24
	v_mul_f32_e32 v23, v23, v25
	v_cvt_pk_bf16_f32 v18, v18, v19
	v_cvt_pk_bf16_f32 v19, v22, v23
	v_mov_b32_e32 v114, v18
	v_mov_b32_e32 v115, v19
	v_mul_f32_e32 v18, v26, v34
	v_mul_f32_e32 v19, v27, v34
	v_lshlrev_b32_e32 v22, 16, v42
	v_and_b32_e32 v23, 0xffff0000, v42
	v_mul_f32_e32 v18, v18, v22
	v_mul_f32_e32 v19, v19, v23
	v_mul_f32_e32 v22, v28, v34
	v_mul_f32_e32 v23, v29, v34
	v_lshlrev_b32_e32 v24, 16, v43
	v_and_b32_e32 v25, 0xffff0000, v43
	v_mul_f32_e32 v22, v22, v24
	v_mul_f32_e32 v23, v23, v25
	v_cvt_pk_bf16_f32 v18, v18, v19
	v_cvt_pk_bf16_f32 v19, v22, v23
	v_mov_b32_e32 v116, v18
	v_mov_b32_e32 v117, v19
	v_mul_f32_e32 v18, v30, v34
	v_mul_f32_e32 v19, v31, v34
	v_lshlrev_b32_e32 v22, 16, v44
	v_and_b32_e32 v23, 0xffff0000, v44
	v_mul_f32_e32 v18, v18, v22
	v_mul_f32_e32 v19, v19, v23
	v_mul_f32_e32 v22, v32, v34
	v_mul_f32_e32 v23, v33, v34
	v_lshlrev_b32_e32 v24, 16, v45
	v_and_b32_e32 v25, 0xffff0000, v45
	v_mul_f32_e32 v22, v22, v24
	v_mul_f32_e32 v23, v23, v25
	v_cvt_pk_bf16_f32 v18, v18, v19
	v_cvt_pk_bf16_f32 v19, v22, v23
	v_mov_b32_e32 v118, v18
	v_mov_b32_e32 v119, v19
	v_lshlrev_b32_e32 v18, 16, v46
	v_and_b32_e32 v19, 0xffff0000, v46
	v_mul_f32_e32 v2, v2, v18
	v_mul_f32_e32 v3, v3, v19
	v_lshlrev_b32_e32 v18, 16, v47
	v_and_b32_e32 v19, 0xffff0000, v47
	v_mul_f32_e32 v4, v4, v18
	v_mul_f32_e32 v5, v5, v19
	v_cvt_pk_bf16_f32 v2, v2, v3
	v_cvt_pk_bf16_f32 v3, v4, v5
	v_mov_b32_e32 v120, v2
	v_mov_b32_e32 v121, v3
	v_mul_f32_e32 v2, v6, v34
	v_mul_f32_e32 v3, v7, v34
	v_lshlrev_b32_e32 v4, 16, v48
	v_and_b32_e32 v5, 0xffff0000, v48
	v_mul_f32_e32 v2, v2, v4
	v_mul_f32_e32 v3, v3, v5
	v_mul_f32_e32 v4, v8, v34
	v_mul_f32_e32 v5, v9, v34
	v_lshlrev_b32_e32 v6, 16, v49
	v_and_b32_e32 v7, 0xffff0000, v49
	v_mul_f32_e32 v4, v4, v6
	v_mul_f32_e32 v5, v5, v7
	v_cvt_pk_bf16_f32 v2, v2, v3
	v_cvt_pk_bf16_f32 v3, v4, v5
	v_mov_b32_e32 v122, v2
	v_mov_b32_e32 v123, v3
	v_mul_f32_e32 v2, v10, v34
	v_mul_f32_e32 v3, v11, v34
	v_lshlrev_b32_e32 v4, 16, v50
	v_and_b32_e32 v5, 0xffff0000, v50
	v_mul_f32_e32 v2, v2, v4
	v_mul_f32_e32 v3, v3, v5
	v_mul_f32_e32 v4, v12, v34
	v_mul_f32_e32 v5, v13, v34
	v_lshlrev_b32_e32 v6, 16, v51
	v_and_b32_e32 v7, 0xffff0000, v51
	v_mul_f32_e32 v4, v4, v6
	v_mul_f32_e32 v5, v5, v7
	v_cvt_pk_bf16_f32 v2, v2, v3
	v_cvt_pk_bf16_f32 v3, v4, v5
	v_mov_b32_e32 v124, v2
	v_mov_b32_e32 v125, v3
	v_mul_f32_e32 v2, v14, v34
	v_mul_f32_e32 v3, v15, v34
	v_lshlrev_b32_e32 v4, 16, v38
	v_and_b32_e32 v5, 0xffff0000, v38
	v_mul_f32_e32 v2, v2, v4
	v_mul_f32_e32 v3, v3, v5
	v_mul_f32_e32 v4, v16, v34
	v_mul_f32_e32 v5, v17, v34
	v_lshlrev_b32_e32 v6, 16, v39
	v_and_b32_e32 v7, 0xffff0000, v39
	v_mul_f32_e32 v4, v4, v6
	v_mul_f32_e32 v5, v5, v7
	v_cvt_pk_bf16_f32 v2, v2, v3
	v_cvt_pk_bf16_f32 v3, v4, v5
	v_mov_b32_e32 v126, v2
	v_mov_b32_e32 v127, v3
	v_mbcnt_lo_u32_b32 v130, -1, 0
	v_mbcnt_hi_u32_b32 v130, -1, v130
	v_and_b32_e32 v130, 32, v130
	v_lshrrev_b32_e32 v130, 2, v130
	v_mov_b32_e32 v131, 0
	v_lshl_add_u64 v[128:129], v[20:21], 0, v[130:131]
	v_permlane32_swap_b32_e32 v112, v114
	v_permlane32_swap_b32_e32 v113, v115
	global_store_dwordx4 v[128:129], v[112:115], off offset:1024
	v_permlane32_swap_b32_e32 v116, v118
	v_permlane32_swap_b32_e32 v117, v119
	global_store_dwordx4 v[128:129], v[116:119], off offset:1056
	v_permlane32_swap_b32_e32 v120, v122
	v_permlane32_swap_b32_e32 v121, v123
	global_store_dwordx4 v[128:129], v[120:123], off offset:1088
	v_permlane32_swap_b32_e32 v124, v126
	v_permlane32_swap_b32_e32 v125, v127
	global_store_dwordx4 v[128:129], v[124:127], off offset:1120

; __device__ __forceinline__ unsigned cvt_pk_bf16(float lo, float hi) { f32x2_t v = {lo, hi}; bf16x2_t b = __builtin_convertvector(v, bf16x2_t); return __builtin_bit_cast(unsigned, b); }
; __device__ __forceinline__ float fast_rcp(float x) { return __builtin_amdgcn_rcpf(x); }
; __device__ __forceinline__ float swap_sum(float v) { auto rr = __builtin_amdgcn_permlane32_swap(__float_as_uint(v), __float_as_uint(v), false, false); return __uint_as_float(rr[0]) + __uint_as_float(rr[1]); }
; #define UNIT_END_BAR() asm volatile("s_waitcnt lgkmcnt(0)\n\ts_barrier" ::: "memory")
; __device__ __forceinline__ void moba_partial_store(const f32x16& o0, const f32x16& o1, float m, float l, float slope2, int t, int j, int rs, int b, int h, int hh, bf16_t* PO, float* PML) {
;     const float lt = swap_sum(l), inv = fast_rcp(lt);
;     const size_t pidx = (((size_t)b * SEQ + t) * 8 + h) * 3 + rs;
;     bf16_t* po = PO + pidx * 64;
; #pragma unroll
;     for (int d0 = 0; d0 < 2; ++d0)
; #pragma unroll
;         for (int g = 0; g < 4; ++g) { const int d = 32 * d0 + 8 * g + 4 * hh; const f32x16& o = d0 ? o1 : o0;
;             u32x2 w; w.x = cvt_pk_bf16(o[4 * g] * inv, o[4 * g + 1] * inv); w.y = cvt_pk_bf16(o[4 * g + 2] * inv, o[4 * g + 3] * inv); *(u32x2*)(po + d) = w; }
;     if (hh == 0) { PML[pidx * 2] = m - slope2 * (float)(t - j * 256); PML[pidx * 2 + 1] = lt; }
; }
; __device__ __forceinline__ void moba_sel_unit(LAS char* lds, int bh, int j, int chunk, int n, const bf16_t* H, const unsigned* lists, bf16_t* PO, float* PML, int tid) {
;     ...
;     UNIT_END_BAR();
;     if (validA) moba_partial_store(oA0, oA1, mA, lA, slope2, tA, j, rsA, b, h, hh, PO, PML);
;     if (validB) moba_partial_store(oB0, oB1, mB, lB, slope2, tB, j, rsB, b, h, hh, PO, PML);
.LBB0_496:
	s_lshl_b32 s1, s1, 8
	s_and_saveexec_b64 s[18:19], s[46:47]
	s_cbranch_execz .LBB0_499
	v_mov_b32_e32 v0, v154
	s_nop 1
	v_permlane32_swap_b32_e32 v154, v0
	v_add_f32_e32 v3, v154, v0
	s_lshl_b64 s[4:5], s[28:29], 17
	v_lshlrev_b32_sdwa v0, v241, v137 dst_sel:DWORD dst_unused:UNUSED_PAD src0_sel:DWORD src1_sel:WORD_0
	v_rcp_f32_e32 v2, v3
	v_lshl_add_u64 v[6:7], s[4:5], 0, v[0:1]
	v_lshrrev_b32_e32 v4, 16, v137
	v_or_b32_e32 v0, s0, v6
	v_mov_b32_e32 v5, v1
	v_mad_u64_u32 v[4:5], s[4:5], v0, 3, v[4:5]
	v_mad_i32_i24 v5, v7, 3, v5
	v_lshlrev_b64 v[6:7], 7, v[4:5]
	v_lshl_add_u64 v[6:7], v[152:153], 0, v[6:7]
	v_mbcnt_lo_u32_b32 v110, -1, 0
	v_mbcnt_hi_u32_b32 v110, -1, v110
	v_and_b32_e32 v110, 32, v110
	v_lshrrev_b32_e32 v110, 2, v110
	v_mov_b32_e32 v111, 0
	v_lshl_add_u64 v[108:109], v[6:7], 0, v[110:111]
	v_mul_f32_e32 v96, v32, v2
	v_mul_f32_e32 v97, v33, v2
	v_mul_f32_e32 v98, v34, v2
	v_mul_f32_e32 v99, v35, v2
	v_cvt_pk_bf16_f32 v100, v96, v97
	v_cvt_pk_bf16_f32 v101, v98, v99
	v_mul_f32_e32 v96, v36, v2
	v_mul_f32_e32 v97, v37, v2
	v_mul_f32_e32 v98, v38, v2
	v_mul_f32_e32 v99, v39, v2
	v_cvt_pk_bf16_f32 v102, v96, v97
	v_cvt_pk_bf16_f32 v103, v98, v99
	s_nop 1
	v_permlane32_swap_b32_e32 v100, v102
	v_permlane32_swap_b32_e32 v101, v103
	global_store_dwordx4 v[108:109], v[100:103], off
	v_mul_f32_e32 v96, v40, v2
	v_mul_f32_e32 v97, v41, v2
	v_mul_f32_e32 v98, v42, v2
	v_mul_f32_e32 v99, v43, v2
	v_cvt_pk_bf16_f32 v104, v96, v97
	v_cvt_pk_bf16_f32 v105, v98, v99
	v_mul_f32_e32 v96, v44, v2
	v_mul_f32_e32 v97, v45, v2
	v_mul_f32_e32 v98, v46, v2
	v_mul_f32_e32 v99, v47, v2
	v_cvt_pk_bf16_f32 v106, v96, v97
	v_cvt_pk_bf16_f32 v107, v98, v99
	s_nop 1
	v_permlane32_swap_b32_e32 v104, v106
	v_permlane32_swap_b32_e32 v105, v107
	global_store_dwordx4 v[108:109], v[104:107], off offset:32
	v_mul_f32_e32 v96, v16, v2
	v_mul_f32_e32 v97, v17, v2
	v_mul_f32_e32 v98, v18, v2
	v_mul_f32_e32 v99, v19, v2
	v_cvt_pk_bf16_f32 v100, v96, v97
	v_cvt_pk_bf16_f32 v101, v98, v99
	v_mul_f32_e32 v96, v20, v2
	v_mul_f32_e32 v97, v21, v2
	v_mul_f32_e32 v98, v22, v2
	v_mul_f32_e32 v99, v23, v2
	v_cvt_pk_bf16_f32 v102, v96, v97
	v_cvt_pk_bf16_f32 v103, v98, v99
	s_nop 1
	v_permlane32_swap_b32_e32 v100, v102
	v_permlane32_swap_b32_e32 v101, v103
	global_store_dwordx4 v[108:109], v[100:103], off offset:64
	v_mul_f32_e32 v96, v24, v2
	v_mul_f32_e32 v97, v25, v2
	v_mul_f32_e32 v98, v26, v2
	v_mul_f32_e32 v99, v27, v2
	v_cvt_pk_bf16_f32 v104, v96, v97
	v_cvt_pk_bf16_f32 v105, v98, v99
	v_mul_f32_e32 v96, v28, v2
	v_mul_f32_e32 v97, v29, v2
	v_mul_f32_e32 v98, v30, v2
	v_mul_f32_e32 v99, v31, v2
	v_cvt_pk_bf16_f32 v106, v96, v97
	v_cvt_pk_bf16_f32 v107, v98, v99
	s_nop 1
	v_permlane32_swap_b32_e32 v104, v106
	v_permlane32_swap_b32_e32 v105, v107
	global_store_dwordx4 v[108:109], v[104:107], off offset:96
	s_and_b64 exec, exec, s[78:79]
	s_cbranch_execz .LBB0_499
	v_sub_u32_sdwa v0, v137, s1 dst_sel:DWORD dst_unused:UNUSED_PAD src0_sel:WORD_0 src1_sel:DWORD
	v_cvt_f32_i32_e32 v0, v0
	v_readlane_b32 s4, v252, 9
	v_readlane_b32 s5, v252, 10
	v_fma_f32 v2, -v132, v0, v134
	s_nop 0
	v_lshl_add_u64 v[4:5], v[4:5], 3, s[4:5]
	global_store_dwordx2 v[4:5], v[2:3], off

; #define LAS __attribute__((address_space(3)))
; __device__ __forceinline__ unsigned cvt_pk_bf16(float lo, float hi) { f32x2_t v = {lo, hi}; bf16x2_t b = __builtin_convertvector(v, bf16x2_t); return __builtin_bit_cast(unsigned, b); }
; __device__ __forceinline__ float bf_lo(unsigned w) { return __uint_as_float(w << 16); }
; __device__ __forceinline__ float bf_hi(unsigned w) { return __uint_as_float(w & 0xffff0000u); }
; __device__ __forceinline__ void moba_own_unit(LAS char* lds, int bh, int jblk, const bf16_t* H, const bf16_t* PO, const float* PML, bf16_t* U, int tid) {
;     ...
;         for (int g = 0; g < 4; ++g) { const int d = 32 * d0 + 8 * g + 4 * hh; const f32x16& o = d0 ? o1 : o0;
;             float a0 = o[4 * g] * wown, a1 = o[4 * g + 1] * wown, a2 = o[4 * g + 2] * wown, a3 = o[4 * g + 3] * wown;
; #pragma unroll
;             for (int s = 0; s < 3; ++s) if (s < nsel) { const u32x2 pv = *(const u32x2*)(PO + (pidx + s) * 64 + d); a0 += wi[s] * bf_lo(pv.x); a1 += wi[s] * bf_hi(pv.x); a2 += wi[s] * bf_lo(pv.y); a3 += wi[s] * bf_hi(pv.y); }
;             const u32x2 z = zr.z[d0][g];
;             u32x2 w; w.x = cvt_pk_bf16(a0 * inv * bf_lo(z.x), a1 * inv * bf_hi(z.x)); w.y = cvt_pk_bf16(a2 * inv * bf_lo(z.y), a3 * inv * bf_hi(z.y));
;             *(u32x2*)(urow + d) = w; }
; __global__ void __launch_bounds__(512, 2) hybrid_fwd(Args a_unused) {
;     ...
;           for (int u = bid; u < 1024; u += G) moba_own_unit((LAS char*)lds, u & 15, u >> 4, (const bf16_t*)(ws + WS_H), (const bf16_t*)(ws + WS_PO), (const float*)(ws + WS_PML), (bf16_t*)(ws + WS_U), tid); }
.LBB0_631:
	v_mul_f32_e32 v4, v34, v4
	v_mul_f32_e32 v5, v35, v5
	v_lshlrev_b32_e32 v6, 16, v120
	v_and_b32_e32 v7, 0xffff0000, v120
	v_mul_f32_e32 v4, v4, v6
	v_mul_f32_e32 v5, v5, v7
	v_mul_f32_e32 v2, v34, v2
	v_mul_f32_e32 v3, v35, v3
	v_lshlrev_b32_e32 v6, 16, v121
	v_and_b32_e32 v7, 0xffff0000, v121
	v_mul_f32_e32 v2, v2, v6
	v_mul_f32_e32 v3, v3, v7
	s_add_i32 s23, s23, s56
	v_cvt_pk_bf16_f32 v4, v4, v5
	v_cvt_pk_bf16_f32 v5, v2, v3
	s_cmpk_gt_i32 s23, 0x3ff
	v_mov_b32_e32 v86, v4
	v_mov_b32_e32 v87, v5
	v_mbcnt_lo_u32_b32 v160, -1, 0
	v_mbcnt_hi_u32_b32 v160, -1, v160
	v_and_b32_e32 v160, 32, v160
	v_lshrrev_b32_e32 v160, 2, v160
	v_mov_b32_e32 v161, 0
	v_lshl_add_u64 v[158:159], v[22:23], 0, v[160:161]
	v_permlane32_swap_b32_e32 v48, v50
	v_permlane32_swap_b32_e32 v49, v51
	global_store_dwordx4 v[158:159], v[48:51], off
	v_permlane32_swap_b32_e32 v60, v62
	v_permlane32_swap_b32_e32 v61, v63
	global_store_dwordx4 v[158:159], v[60:63], off offset:32
	v_permlane32_swap_b32_e32 v72, v74
	v_permlane32_swap_b32_e32 v73, v75
	global_store_dwordx4 v[158:159], v[72:75], off offset:64
	v_permlane32_swap_b32_e32 v84, v86
	v_permlane32_swap_b32_e32 v85, v87
	global_store_dwordx4 v[158:159], v[84:87], off offset:96
	s_waitcnt lgkmcnt(0)
	s_barrier
	s_cbranch_scc1 .LBB0_773

; __device__ __forceinline__ float bf_lo(unsigned w) { return __uint_as_float(w << 16); }
; __device__ __forceinline__ float bf_hi(unsigned w) { return __uint_as_float(w & 0xffff0000u); }
; __device__ __forceinline__ float fast_exp2(float x) { return __builtin_amdgcn_exp2f(x); }
; __device__ __forceinline__ float fast_rcp(float x) { return __builtin_amdgcn_rcpf(x); }
; __device__ __forceinline__ float swap_sum(float v) { auto rr = __builtin_amdgcn_permlane32_swap(__float_as_uint(v), __float_as_uint(v), false, false); return __uint_as_float(rr[0]) + __uint_as_float(rr[1]); }
; #define UNIT_END_BAR() asm volatile("s_waitcnt lgkmcnt(0)\n\ts_barrier" ::: "memory")
; __device__ __forceinline__ void moba_own_unit(LAS char* lds, int bh, int jblk, const bf16_t* H, const bf16_t* PO, const float* PML, bf16_t* U, int tid) {
;     ...
;     UNIT_END_BAR();
;     ...
;     const float lt = swap_sum(l);
;     const float mown = m - slope2 * (float)(qpos - s0);
;     float M = mown;
; #pragma unroll
;     for (int s = 0; s < 3; ++s) if (s < nsel) M = fmaxf(M, mi[s]);
;     const float wown = fast_exp2(mown - M); float den = wown * lt;
; #pragma unroll
;     for (int s = 0; s < 3; ++s) { wi[s] = (s < nsel) ? wi[s] * fast_exp2(mi[s] - M) : 0.f; den += wi[s]; }
;     const float inv = fast_rcp(den);
;     ...
;             for (int s = 0; s < 3; ++s) if (s < nsel) { const u32x2 pv = *(const u32x2*)(PO + (pidx + s) * 64 + d); a0 += wi[s] * bf_lo(pv.x); a1 += wi[s] * bf_hi(pv.x); a2 += wi[s] * bf_lo(pv.y); a3 += wi[s] * bf_hi(pv.y); }
.LBB0_725:
	v_subrev_u32_e32 v36, s24, v144
	v_cvt_f32_i32_e32 v36, v36
	v_max_f32_e32 v37, v146, v146
	v_max_f32_e32 v38, v140, v140
	v_fma_f32 v36, -v148, v36, v122
	v_max_f32_e32 v37, v36, v37
	v_cndmask_b32_e64 v37, v36, v37, s[40:41]
	v_max_f32_e32 v38, v37, v38
	v_cndmask_b32_e64 v37, v37, v38, s[42:43]
	v_max_f32_e32 v38, v142, v142
	v_max_f32_e32 v38, v37, v38
	v_cndmask_b32_e64 v37, v37, v38, s[44:45]
	v_sub_f32_e32 v36, v36, v37
	v_exp_f32_e32 v38, v36
	v_sub_f32_e32 v36, v146, v37
	v_exp_f32_e32 v36, v36
	v_mov_b32_e32 v35, v34
	s_nop 1
	v_permlane32_swap_b32_e32 v34, v35
	v_mul_f32_e32 v36, v147, v36
	v_mul_f32_e32 v42, v18, v38
	v_mul_f32_e32 v43, v19, v38
	v_mul_f32_e32 v40, v20, v38
	v_mul_f32_e32 v41, v21, v38
	s_and_b64 vcc, exec, s[40:41]
	s_cbranch_vccz .Lown_pf_done
	v_mbcnt_lo_u32_b32 v160, -1, 0
	v_mbcnt_hi_u32_b32 v160, -1, v160
	v_and_b32_e32 v160, 32, v160
	v_lshrrev_b32_e32 v160, 2, v160
	v_mov_b32_e32 v161, 0
	v_mad_u64_u32 v[96:97], s[4:5], v145, s10, v[102:103]
	v_mov_b32_e32 v98, v97
	v_mad_u64_u32 v[98:99], s[4:5], v123, s10, v[98:99]
	v_mov_b32_e32 v150, v96
	v_mov_b32_e32 v151, v98
	v_lshl_add_u64 v[150:151], v[150:151], 0, v[160:161]
	v_mad_u64_u32 v[96:97], s[4:5], v145, s10, v[106:107]
	v_mov_b32_e32 v98, v97
	v_mad_u64_u32 v[98:99], s[4:5], v123, s10, v[98:99]
	v_mov_b32_e32 v152, v96
	v_mov_b32_e32 v153, v98
	v_lshl_add_u64 v[152:153], v[152:153], 0, v[160:161]
	v_mad_u64_u32 v[96:97], s[4:5], v145, s10, v[110:111]
	v_mov_b32_e32 v98, v97
	v_mad_u64_u32 v[98:99], s[4:5], v123, s10, v[98:99]
	v_mov_b32_e32 v154, v96
	v_mov_b32_e32 v155, v98
	v_lshl_add_u64 v[154:155], v[154:155], 0, v[160:161]
	v_mad_u64_u32 v[96:97], s[4:5], v145, s10, v[114:115]
	v_mov_b32_e32 v98, v97
	v_mad_u64_u32 v[98:99], s[4:5], v123, s10, v[98:99]
	v_mov_b32_e32 v156, v96
	v_mov_b32_e32 v157, v98
	v_lshl_add_u64 v[156:157], v[156:157], 0, v[160:161]
	global_load_dwordx4 v[48:51], v[150:151], off
	global_load_dwordx4 v[60:63], v[152:153], off
	global_load_dwordx4 v[72:75], v[154:155], off
	global_load_dwordx4 v[84:87], v[156:157], off
	s_and_b64 vcc, exec, s[42:43]
	s_cbranch_vccz .Lown_pf_done
	global_load_dwordx4 v[52:55], v[150:151], off offset:128
	global_load_dwordx4 v[64:67], v[152:153], off offset:128
	global_load_dwordx4 v[76:79], v[154:155], off offset:128
	global_load_dwordx4 v[88:91], v[156:157], off offset:128
	s_and_b64 vcc, exec, s[44:45]
	s_cbranch_vccz .Lown_pf_done
	global_load_dwordx4 v[56:59], v[150:151], off offset:256
	global_load_dwordx4 v[68:71], v[152:153], off offset:256
	global_load_dwordx4 v[80:83], v[154:155], off offset:256
	global_load_dwordx4 v[92:95], v[156:157], off offset:256
